# Serialized load-use chains batched: dilated 3-branch combine (32 loads up front), L0 subln combine (4 rows per iteration), prologue x->h / memn loops and final RMSNorm (all chunk loads of a row issued
# speedup vs baseline: 1.0131x; 1.0024x over previous
; #define LAS __attribute__((address_space(3)))
; __global__ void __launch_bounds__(NWAVES * 64, 2) fwd_megakernel(Args args) {
;     ...
;         const int gw = bid * NWAVES + wave, ngw = G * NWAVES;
;         LAS float* scr = (LAS float*)(lds + wave * 16640);
;         convert_slot(args.in, WB, 0, gw, ngw, scr, lane);
;         const float* g0 = args.in[I_F1N];
;         for (int r = gw; r < SEQ; r += ngw) {
;             const f32x4* xr = (const f32x4*)(args.in[I_X] + (size_t)r * DM) + lane;
;             float s = 0.f;
; #pragma unroll
;             for (int j = 0; j < 8; ++j) {
;                 const f32x4 v = xr[64 * j]; const f32x4 gg = *((const f32x4*)g0 + lane + 64 * j);
.LBB0_25:
	v_and_b32_e32 v1, 63, v1
	s_cmpk_gt_i32 s8, 0x1fff
	s_waitcnt vmcnt(23)
	v_lshlrev_b32_e32 v2, 4, v1
	s_waitcnt vmcnt(19)
	v_mbcnt_lo_u32_b32 v18, -1, 0
	s_cbranch_scc1 .LBB0_30
	v_readlane_b32 s44, v251, 2
	v_mbcnt_hi_u32_b32 v6, -1, v18
	v_mov_b32_e32 v3, 0
	v_readlane_b32 s48, v251, 6
	v_readlane_b32 s49, v251, 7
	v_and_b32_e32 v8, 64, v6
	v_xor_b32_e32 v7, 32, v6
	v_lshl_add_u64 v[4:5], s[48:49], 0, v[2:3]
	v_add_u32_e32 v8, 64, v8
	s_mov_b64 s[10:11], 0x1400
	v_cmp_lt_i32_e32 vcc, v7, v8
	v_lshl_add_u64 v[8:9], v[4:5], 0, s[10:11]
	s_mov_b64 s[10:11], 0x1800
	v_lshl_add_u64 v[10:11], v[4:5], 0, s[10:11]
	s_mov_b64 s[10:11], 0x1c00
	s_ashr_i32 s9, s8, 31
	v_lshl_add_u64 v[12:13], v[4:5], 0, s[10:11]
	s_lshl_b64 s[10:11], s[8:9], 2
	s_add_u32 s17, s10, 0x40000
	s_addc_u32 s18, s11, 0
	s_ashr_i32 s93, s92, 31
	s_lshl_b64 s[10:11], s[92:93], 2
	s_lshl_b64 s[12:13], s[8:9], 13
	v_readlane_b32 s45, v251, 3
	s_add_u32 s12, s44, s12
	s_addc_u32 s13, s45, s13
	v_cndmask_b32_e32 v6, v6, v7, vcc
	s_mov_b64 s[0:1], 0x1000
	v_lshl_add_u64 v[14:15], s[12:13], 0, v[2:3]
	v_lshlrev_b32_e32 v19, 2, v6
	v_lshl_add_u64 v[6:7], v[4:5], 0, s[0:1]
	v_lshl_add_u64 v[14:15], v[14:15], 0, s[0:1]
	s_lshl_b64 s[0:1], s[8:9], 12
	v_cmp_eq_u32_e32 vcc, 0, v1
	s_lshl_b64 s[12:13], s[92:93], 13
	v_lshl_or_b32 v16, v1, 3, s0
	v_mov_b32_e32 v17, s1
	s_lshl_b64 s[14:15], s[92:93], 12
	s_mov_b32 s9, 0x19900000
	s_mov_b32 s19, s8
	v_readlane_b32 s46, v251, 4
	v_readlane_b32 s47, v251, 5
	v_readlane_b32 s50, v251, 8
	v_readlane_b32 s51, v251, 9
	v_readlane_b32 s52, v251, 10
	v_readlane_b32 s53, v251, 11
	v_readlane_b32 s54, v251, 12
	v_readlane_b32 s55, v251, 13
	v_readlane_b32 s56, v251, 14
	v_readlane_b32 s57, v251, 15
	v_readlane_b32 s58, v251, 16
	v_readlane_b32 s59, v251, 17
	s_waitcnt vmcnt(0)
	global_load_dwordx4 v[80:83], v[4:5], off
	global_load_dwordx4 v[84:87], v[4:5], off offset:1024
	global_load_dwordx4 v[88:91], v[4:5], off offset:2048
	global_load_dwordx4 v[92:95], v[4:5], off offset:3072
	global_load_dwordx4 v[96:99], v[6:7], off
	global_load_dwordx4 v[100:103], v[8:9], off
	global_load_dwordx4 v[104:107], v[10:11], off
	global_load_dwordx4 v[108:111], v[12:13], off
	s_branch .LBB0_28

; __device__ __forceinline__ unsigned pk2(float lo, float hi) { f32x2 v = {lo, hi}; bf16x2_t b = __builtin_convertvector(v, bf16x2_t); return __builtin_bit_cast(unsigned, b); }
; __global__ void __launch_bounds__(NWAVES * 64, 2) fwd_megakernel(Args args) {
;     ...
;         for (int r = gw; r < SEQ; r += ngw) {
;             const f32x4* xr = (const f32x4*)(args.in[I_X] + (size_t)r * DM) + lane;
;             float s = 0.f;
; #pragma unroll
;             for (int j = 0; j < 8; ++j) {
;                 const f32x4 v = xr[64 * j]; const f32x4 gg = *((const f32x4*)g0 + lane + 64 * j);
;                 s += (v[0] * v[0] + v[1] * v[1]) + (v[2] * v[2] + v[3] * v[3]);
;                 u32x2 w; w.x = pk2(v[0] * gg[0], v[1] * gg[1]); w.y = pk2(v[2] * gg[2], v[3] * gg[3]);
;                 *((u32x2*)(H + (size_t)r * DM) + lane + 64 * j) = w;
;             }
;             s = wave_sum(s);
;             if (lane == 0) SS[r] = s;
;         }
;         for (int r = gw; r < DEPTH * NMEM; r += ngw) {
;             const int l = r / NMEM, mr = r % NMEM;
;             const f32x4* xr = (const f32x4*)(args.in[I_MEM] + (size_t)mr * DM) + lane;
;             const float* gk = args.in[I_MKVN] + (size_t)l * DM;
.LBB0_28:
	s_waitcnt lgkmcnt(0)
	global_load_dwordx4 v[20:23], v[14:15], off offset:-4096
	global_load_dwordx4 v[24:27], v[14:15], off offset:-3072
	global_load_dwordx4 v[28:31], v[14:15], off offset:-2048
	global_load_dwordx4 v[32:35], v[14:15], off offset:-1024
	global_load_dwordx4 v[36:39], v[14:15], off
	global_load_dwordx4 v[40:43], v[14:15], off offset:1024
	global_load_dwordx4 v[44:47], v[14:15], off offset:2048
	global_load_dwordx4 v[48:51], v[14:15], off offset:3072
	v_lshl_add_u64 v[52:53], s[40:41], 0, v[16:17]
	v_add_co_u32_e64 v56, s[0:1], s9, v52
	s_nop 1
	v_addc_co_u32_e64 v57, s[0:1], 0, v53, s[0:1]
	s_waitcnt vmcnt(0)
	v_mul_f32_e32 v112, v21, v21
	v_mul_f32_e32 v113, v23, v23
	v_fmac_f32_e32 v112, v20, v20
	v_fmac_f32_e32 v113, v22, v22
	v_add_f32_e32 v112, v112, v113
	v_mov_b32_e32 v114, v112
	v_pk_mul_f32 v[20:21], v[20:21], v[80:81]
	v_pk_mul_f32 v[22:23], v[22:23], v[82:83]
	v_cvt_pk_bf16_f32 v20, v20, v21
	v_cvt_pk_bf16_f32 v21, v22, v23
	global_store_dwordx2 v[56:57], v[20:21], off
	v_mul_f32_e32 v112, v25, v25
	v_mul_f32_e32 v113, v27, v27
	v_fmac_f32_e32 v112, v24, v24
	v_fmac_f32_e32 v113, v26, v26
	v_add_f32_e32 v112, v112, v113
	v_add_f32_e32 v114, v114, v112
	v_pk_mul_f32 v[24:25], v[24:25], v[84:85]
	v_pk_mul_f32 v[26:27], v[26:27], v[86:87]
	v_cvt_pk_bf16_f32 v24, v24, v25
	v_cvt_pk_bf16_f32 v25, v26, v27
	global_store_dwordx2 v[56:57], v[24:25], off offset:512
	v_mul_f32_e32 v112, v29, v29
	v_mul_f32_e32 v113, v31, v31
	v_fmac_f32_e32 v112, v28, v28
	v_fmac_f32_e32 v113, v30, v30
	v_add_f32_e32 v112, v112, v113
	v_add_f32_e32 v114, v114, v112
	v_pk_mul_f32 v[28:29], v[28:29], v[88:89]
	v_pk_mul_f32 v[30:31], v[30:31], v[90:91]
	v_cvt_pk_bf16_f32 v28, v28, v29
	v_cvt_pk_bf16_f32 v29, v30, v31
	global_store_dwordx2 v[56:57], v[28:29], off offset:1024
	v_mul_f32_e32 v112, v33, v33
	v_mul_f32_e32 v113, v35, v35
	v_fmac_f32_e32 v112, v32, v32
	v_fmac_f32_e32 v113, v34, v34
	v_add_f32_e32 v112, v112, v113
	v_add_f32_e32 v114, v114, v112
	v_pk_mul_f32 v[32:33], v[32:33], v[92:93]
	v_pk_mul_f32 v[34:35], v[34:35], v[94:95]
	v_cvt_pk_bf16_f32 v32, v32, v33
	v_cvt_pk_bf16_f32 v33, v34, v35
	global_store_dwordx2 v[56:57], v[32:33], off offset:1536
	v_mul_f32_e32 v112, v37, v37
	v_mul_f32_e32 v113, v39, v39
	v_fmac_f32_e32 v112, v36, v36
	v_fmac_f32_e32 v113, v38, v38
	v_add_f32_e32 v112, v112, v113
	v_add_f32_e32 v114, v114, v112
	v_pk_mul_f32 v[36:37], v[36:37], v[96:97]
	v_pk_mul_f32 v[38:39], v[38:39], v[98:99]
	v_cvt_pk_bf16_f32 v36, v36, v37
	v_cvt_pk_bf16_f32 v37, v38, v39
	global_store_dwordx2 v[56:57], v[36:37], off offset:2048
	v_mul_f32_e32 v112, v41, v41
	v_mul_f32_e32 v113, v43, v43
	v_fmac_f32_e32 v112, v40, v40
	v_fmac_f32_e32 v113, v42, v42
	v_add_f32_e32 v112, v112, v113
	v_add_f32_e32 v114, v114, v112
	v_pk_mul_f32 v[40:41], v[40:41], v[100:101]
	v_pk_mul_f32 v[42:43], v[42:43], v[102:103]
	v_cvt_pk_bf16_f32 v40, v40, v41
	v_cvt_pk_bf16_f32 v41, v42, v43
	global_store_dwordx2 v[56:57], v[40:41], off offset:2560
	v_mul_f32_e32 v112, v45, v45
	v_mul_f32_e32 v113, v47, v47
	v_fmac_f32_e32 v112, v44, v44
	v_fmac_f32_e32 v113, v46, v46
	v_add_f32_e32 v112, v112, v113
	v_add_f32_e32 v114, v114, v112
	v_pk_mul_f32 v[44:45], v[44:45], v[104:105]
	v_pk_mul_f32 v[46:47], v[46:47], v[106:107]
	v_cvt_pk_bf16_f32 v44, v44, v45
	v_cvt_pk_bf16_f32 v45, v46, v47
	global_store_dwordx2 v[56:57], v[44:45], off offset:3072
	v_mul_f32_e32 v112, v49, v49
	v_mul_f32_e32 v113, v51, v51
	v_fmac_f32_e32 v112, v48, v48
	v_fmac_f32_e32 v113, v50, v50
	v_add_f32_e32 v112, v112, v113
	v_add_f32_e32 v114, v114, v112
	v_pk_mul_f32 v[48:49], v[48:49], v[108:109]
	v_pk_mul_f32 v[50:51], v[50:51], v[110:111]
	v_cvt_pk_bf16_f32 v48, v48, v49
	v_cvt_pk_bf16_f32 v49, v50, v51
	global_store_dwordx2 v[56:57], v[48:49], off offset:3584
	v_mov_b32_e32 v20, v114
	ds_swizzle_b32 v21, v20 offset:swizzle(SWAP,1)
	s_waitcnt lgkmcnt(0)
	v_add_f32_e32 v20, v20, v21
	ds_swizzle_b32 v21, v20 offset:swizzle(SWAP,2)
	s_waitcnt lgkmcnt(0)
	v_add_f32_e32 v20, v20, v21
	ds_swizzle_b32 v21, v20 offset:swizzle(SWAP,4)
	s_waitcnt lgkmcnt(0)
	v_add_f32_e32 v20, v20, v21
	ds_swizzle_b32 v21, v20 offset:swizzle(SWAP,8)
	s_waitcnt lgkmcnt(0)
	v_add_f32_e32 v20, v20, v21
	ds_swizzle_b32 v21, v20 offset:swizzle(SWAP,16)
	s_waitcnt lgkmcnt(0)
	v_add_f32_e32 v20, v20, v21
	ds_bpermute_b32 v21, v19, v20
	s_and_saveexec_b64 s[0:1], vcc
	s_cbranch_execz .LBB0_27
	s_add_u32 s20, s40, s17
	s_addc_u32 s21, s41, s18
	s_waitcnt lgkmcnt(0)
	v_add_f32_e32 v20, v20, v21
	global_store_dword v3, v20, s[20:21]
	s_branch .LBB0_27
.LBB0_30:
	s_add_u32 s0, s40, 0x24a00000
	s_addc_u32 s1, s41, 0
	v_writelane_b32 v251, s0, 52
	s_cmpk_gt_i32 s8, 0x1ff
	s_nop 0
	v_writelane_b32 v251, s1, 53
	s_cbranch_scc1 .LBB0_33
	s_waitcnt vmcnt(0)
	v_mbcnt_hi_u32_b32 v6, -1, v18
	v_readlane_b32 s44, v251, 2
	v_and_b32_e32 v8, 64, v6
	v_mov_b32_e32 v3, 0
	v_readlane_b32 s45, v251, 3
	v_readlane_b32 s46, v251, 4
	v_readlane_b32 s47, v251, 5
	v_readlane_b32 s48, v251, 6
	v_readlane_b32 s49, v251, 7
	v_readlane_b32 s50, v251, 8
	v_readlane_b32 s51, v251, 9
	v_readlane_b32 s52, v251, 10
	v_readlane_b32 s53, v251, 11
	v_readlane_b32 s54, v251, 12
	v_readlane_b32 s55, v251, 13
	v_readlane_b32 s56, v251, 14
	v_readlane_b32 s57, v251, 15
	v_readlane_b32 s58, v251, 16
	v_readlane_b32 s59, v251, 17
	v_xor_b32_e32 v7, 32, v6
	v_add_u32_e32 v8, 64, v8
	v_lshl_add_u64 v[4:5], s[46:47], 0, v[2:3]
	v_cmp_lt_i32_e32 vcc, v7, v8
	v_readlane_b32 s44, v251, 34
	v_readlane_b32 s45, v251, 35
	v_cndmask_b32_e32 v6, v6, v7, vcc
	v_readlane_b32 s0, v251, 52
	v_lshlrev_b32_e32 v8, 2, v6
	v_lshl_add_u64 v[6:7], s[44:45], 0, v[2:3]
	v_lshlrev_b32_e32 v2, 3, v1
	v_readlane_b32 s1, v251, 53
	v_mov_b32_e32 v1, 0x358637bd
	v_readlane_b32 s46, v251, 36
	v_lshl_add_u64 v[2:3], s[0:1], 0, v[2:3]
	s_movk_i32 s0, 0x1000
	v_readlane_b32 s47, v251, 37
	v_readlane_b32 s48, v251, 38
	v_readlane_b32 s49, v251, 39
	v_readlane_b32 s50, v251, 40
	v_readlane_b32 s51, v251, 41
	v_readlane_b32 s52, v251, 42
	v_readlane_b32 s53, v251, 43
	v_readlane_b32 s54, v251, 44
	v_readlane_b32 s55, v251, 45
	v_readlane_b32 s56, v251, 46
	v_readlane_b32 s57, v251, 47
	v_readlane_b32 s58, v251, 48
	v_readlane_b32 s59, v251, 49
; __global__ void __launch_bounds__(NWAVES * 64, 2) fwd_megakernel(Args args) {
;     ...
;         for (int r = gw; r < DEPTH * NMEM; r += ngw) {
;             const int l = r / NMEM, mr = r % NMEM;
;             const f32x4* xr = (const f32x4*)(args.in[I_MEM] + (size_t)mr * DM) + lane;
;             const float* gk = args.in[I_MKVN] + (size_t)l * DM;
;             f32x4 v[8]; float s = 0.f;
; #pragma unroll
;             for (int j = 0; j < 8; ++j) { v[j] = xr[64 * j]; s += (v[j][0] * v[j][0] + v[j][1] * v[j][1]) + (v[j][2] * v[j][2] + v[j][3] * v[j][3]); }
;             s = wave_sum(s);
.LBB0_32:
	s_ashr_i32 s9, s8, 31
	s_lshr_b32 s1, s9, 24
	s_add_i32 s1, s8, s1
	s_and_b32 s10, s1, 0xffffff00
	s_sub_i32 s10, s8, s10
	s_ashr_i32 s11, s10, 31
	s_lshl_b64 s[10:11], s[10:11], 13
	s_waitcnt vmcnt(17)
	v_lshl_add_u64 v[28:29], v[4:5], 0, s[10:11]
	global_load_dwordx4 v[10:13], v[28:29], off
	global_load_dwordx4 v[14:17], v[28:29], off offset:1024
	s_waitcnt lgkmcnt(0)
	global_load_dwordx4 v[20:23], v[28:29], off offset:2048
	global_load_dwordx4 v[24:27], v[28:29], off offset:3072
	s_waitcnt vmcnt(18)
	v_add_co_u32_e32 v40, vcc, s0, v28
	s_ashr_i32 s10, s1, 8
	s_nop 0
	v_addc_co_u32_e32 v41, vcc, 0, v29, vcc
	global_load_dwordx4 v[28:31], v[40:41], off
	global_load_dwordx4 v[32:35], v[40:41], off offset:1024
	global_load_dwordx4 v[36:39], v[40:41], off offset:3072
	s_nop 0
	global_load_dwordx4 v[40:43], v[40:41], off offset:2048
	s_ashr_i32 s11, s10, 31
	s_lshl_b64 s[10:11], s[10:11], 13
	s_waitcnt vmcnt(20)
	v_lshl_add_u64 v[48:49], v[6:7], 0, s[10:11]
	global_load_dwordx4 v[44:47], v[48:49], off
	global_load_dwordx4 v[80:83], v[48:49], off offset:1024
	global_load_dwordx4 v[84:87], v[48:49], off offset:2048
	global_load_dwordx4 v[88:91], v[48:49], off offset:3072
	v_add_co_u32_e32 v108, vcc, s0, v48
	s_nop 1
	v_addc_co_u32_e32 v109, vcc, 0, v49, vcc
	global_load_dwordx4 v[92:95], v[108:109], off
	global_load_dwordx4 v[96:99], v[108:109], off offset:1024
	global_load_dwordx4 v[100:103], v[108:109], off offset:2048
	global_load_dwordx4 v[104:107], v[108:109], off offset:3072
	s_lshl_b64 s[10:11], s[8:9], 12
	s_add_i32 s8, s8, s92
	s_cmpk_gt_i32 s8, 0x1ff
	s_waitcnt vmcnt(15)
	v_mov_b32_e32 v52, v11
	s_waitcnt vmcnt(14)
	v_mov_b32_e32 v53, v15
	v_mov_b32_e32 v56, v13
	v_mov_b32_e32 v57, v17
	v_mov_b32_e32 v50, v10
	v_mov_b32_e32 v51, v14
	v_mov_b32_e32 v54, v12
	v_mov_b32_e32 v55, v16
	s_waitcnt vmcnt(13)
	v_pk_mul_f32 v[58:59], v[22:23], v[22:23]
	v_pk_mul_f32 v[60:61], v[20:21], v[20:21]
	v_pk_mul_f32 v[52:53], v[52:53], v[52:53]
	v_pk_mul_f32 v[56:57], v[56:57], v[56:57]
	v_pk_mov_b32 v[66:67], v[60:61], v[58:59] op_sel:[1,0]
	v_mov_b32_e32 v61, v59
	v_pk_fma_f32 v[50:51], v[50:51], v[50:51], v[52:53]
	v_pk_fma_f32 v[52:53], v[54:55], v[54:55], v[56:57]
	s_waitcnt vmcnt(12)
	v_mul_f32_e32 v62, v25, v25
	v_mul_f32_e32 v64, v27, v27
	v_pk_add_f32 v[54:55], v[66:67], v[60:61]
	v_pk_add_f32 v[50:51], v[50:51], v[52:53]
	s_waitcnt vmcnt(11)
	v_mul_f32_e32 v9, v28, v28
	v_mul_f32_e32 v19, v29, v29
	v_mul_f32_e32 v71, v30, v30
	v_mul_f32_e32 v73, v31, v31
	v_pk_fma_f32 v[58:59], v[24:25], v[24:25], v[62:63] op_sel_hi:[1,1,0]
	v_pk_fma_f32 v[62:63], v[26:27], v[26:27], v[64:65] op_sel_hi:[1,1,0]
	v_pk_add_f32 v[52:53], v[54:55], v[54:55] op_sel:[0,1] op_sel_hi:[1,0]
	v_pk_add_f32 v[50:51], v[50:51], v[50:51] op_sel:[0,1] op_sel_hi:[1,0]
	s_waitcnt vmcnt(10)
	v_pk_mul_f32 v[64:65], v[34:35], v[34:35]
	v_pk_mul_f32 v[68:69], v[32:33], v[32:33]
	v_mov_b32_e32 v59, v71
	v_mov_b32_e32 v63, v73
	v_mov_b32_e32 v53, v19
	v_mov_b32_e32 v51, v9
	v_pk_mov_b32 v[56:57], v[68:69], v[64:65] op_sel:[1,0]
	v_mov_b32_e32 v69, v65
	v_pk_add_f32 v[54:55], v[58:59], v[62:63]
	v_pk_add_f32 v[50:51], v[50:51], v[52:53]
	s_waitcnt vmcnt(8)
	v_mul_f32_e32 v70, v41, v41
	v_mul_f32_e32 v72, v43, v43
	v_pk_add_f32 v[56:57], v[56:57], v[68:69]
	v_pk_add_f32 v[50:51], v[50:51], v[54:55]
	v_mul_f32_e32 v74, v36, v36
	v_mul_f32_e32 v75, v37, v37
	v_mul_f32_e32 v76, v38, v38
	v_mul_f32_e32 v77, v39, v39
	v_pk_fma_f32 v[60:61], v[40:41], v[40:41], v[70:71] op_sel_hi:[1,1,0]
	v_pk_fma_f32 v[64:65], v[42:43], v[42:43], v[72:73] op_sel_hi:[1,1,0]
	v_pk_add_f32 v[56:57], v[56:57], v[56:57] op_sel:[0,1] op_sel_hi:[1,0]
	v_pk_add_f32 v[50:51], v[50:51], v[50:51] op_sel:[0,1] op_sel_hi:[1,0]
	v_mov_b32_e32 v61, v76
	v_mov_b32_e32 v65, v77
	v_mov_b32_e32 v57, v75
	v_mov_b32_e32 v51, v74
	v_pk_add_f32 v[58:59], v[60:61], v[64:65]
	v_pk_add_f32 v[50:51], v[50:51], v[56:57]
	v_lshl_add_u64 v[52:53], v[2:3], 0, s[10:11]
	v_pk_add_f32 v[50:51], v[50:51], v[58:59]
	s_nop 0
	v_add_f32_e32 v9, v50, v51
	ds_swizzle_b32 v19, v9 offset:swizzle(SWAP,1)
	s_waitcnt lgkmcnt(0)
; __device__ __forceinline__ unsigned pk2(float lo, float hi) { f32x2 v = {lo, hi}; bf16x2_t b = __builtin_convertvector(v, bf16x2_t); return __builtin_bit_cast(unsigned, b); }
; __global__ void __launch_bounds__(NWAVES * 64, 2) fwd_megakernel(Args args) {
;     ...
;             s = wave_sum(s);
;             const float rs = __builtin_amdgcn_rsqf(s * (1.0f / DM) + EPS);
; #pragma unroll
;             for (int j = 0; j < 8; ++j) {
;                 const f32x4 gg = *((const f32x4*)gk + lane + 64 * j);
;                 u32x2 w; w.x = pk2(v[j][0] * rs * gg[0], v[j][1] * rs * gg[1]); w.y = pk2(v[j][2] * rs * gg[2], v[j][3] * rs * gg[3]);
;                 *((u32x2*)(MEMN + (size_t)r * DM) + lane + 64 * j) = w;
;             }
	v_add_f32_e32 v9, v9, v19
	ds_swizzle_b32 v19, v9 offset:swizzle(SWAP,2)
	s_waitcnt lgkmcnt(0)
	v_add_f32_e32 v9, v9, v19
	ds_swizzle_b32 v19, v9 offset:swizzle(SWAP,4)
	s_waitcnt lgkmcnt(0)
	v_add_f32_e32 v9, v9, v19
	ds_swizzle_b32 v19, v9 offset:swizzle(SWAP,8)
	s_waitcnt lgkmcnt(0)
	v_add_f32_e32 v9, v9, v19
	ds_swizzle_b32 v19, v9 offset:swizzle(SWAP,16)
	s_waitcnt lgkmcnt(0)
	v_add_f32_e32 v9, v9, v19
	ds_bpermute_b32 v19, v8, v9
	s_waitcnt lgkmcnt(0)
	v_add_f32_e32 v9, v9, v19
	v_fmamk_f32 v9, v9, 0x3a000000, v1
	v_rsq_f32_e32 v50, v9
	s_nop 0
	v_pk_mul_f32 v[10:11], v[50:51], v[10:11] op_sel_hi:[0,1]
	v_pk_mul_f32 v[12:13], v[50:51], v[12:13] op_sel_hi:[0,1]
	s_waitcnt vmcnt(7)
	v_pk_mul_f32 v[10:11], v[10:11], v[44:45]
	v_pk_mul_f32 v[12:13], v[12:13], v[46:47]
	v_cvt_pk_bf16_f32 v10, v10, v11
	v_cvt_pk_bf16_f32 v11, v12, v13
	global_store_dwordx2 v[52:53], v[10:11], off
	s_waitcnt vmcnt(7)
	v_mov_b64_e32 v[10:11], v[80:81]
	v_mov_b64_e32 v[12:13], v[82:83]
	v_pk_mul_f32 v[14:15], v[50:51], v[14:15] op_sel_hi:[0,1]
	v_pk_mul_f32 v[16:17], v[50:51], v[16:17] op_sel_hi:[0,1]
	v_pk_mul_f32 v[10:11], v[14:15], v[10:11]
	v_pk_mul_f32 v[12:13], v[16:17], v[12:13]
	v_cvt_pk_bf16_f32 v10, v10, v11
	v_cvt_pk_bf16_f32 v11, v12, v13
	global_store_dwordx2 v[52:53], v[10:11], off offset:512
	s_waitcnt vmcnt(7)
	v_mov_b64_e32 v[10:11], v[84:85]
	v_mov_b64_e32 v[12:13], v[86:87]
	v_pk_mul_f32 v[14:15], v[50:51], v[20:21] op_sel_hi:[0,1]
	v_pk_mul_f32 v[16:17], v[50:51], v[22:23] op_sel_hi:[0,1]
	v_pk_mul_f32 v[20:21], v[50:51], v[26:27] op_sel_hi:[0,1]
	v_pk_mul_f32 v[10:11], v[14:15], v[10:11]
	v_pk_mul_f32 v[12:13], v[16:17], v[12:13]
	v_cvt_pk_bf16_f32 v10, v10, v11
	v_cvt_pk_bf16_f32 v11, v12, v13
	global_store_dwordx2 v[52:53], v[10:11], off offset:1024
	s_waitcnt vmcnt(7)
	v_mov_b64_e32 v[10:11], v[88:89]
	v_mov_b64_e32 v[12:13], v[90:91]
	v_pk_mul_f32 v[16:17], v[50:51], v[24:25] op_sel_hi:[0,1]
	v_add_co_u32_e32 v14, vcc, s0, v48
	v_pk_mul_f32 v[10:11], v[16:17], v[10:11]
	v_pk_mul_f32 v[12:13], v[20:21], v[12:13]
	v_cvt_pk_bf16_f32 v10, v10, v11
	v_cvt_pk_bf16_f32 v11, v12, v13
	v_addc_co_u32_e32 v15, vcc, 0, v49, vcc
	global_store_dwordx2 v[52:53], v[10:11], off offset:1536
	s_waitcnt vmcnt(7)
	v_mov_b64_e32 v[10:11], v[92:93]
	v_mov_b64_e32 v[12:13], v[94:95]
	v_pk_mul_f32 v[16:17], v[50:51], v[28:29] op_sel_hi:[0,1]
	v_pk_mul_f32 v[20:21], v[50:51], v[30:31] op_sel_hi:[0,1]
	v_pk_mul_f32 v[10:11], v[16:17], v[10:11]
	v_pk_mul_f32 v[12:13], v[20:21], v[12:13]
	v_cvt_pk_bf16_f32 v10, v10, v11
	v_cvt_pk_bf16_f32 v11, v12, v13
	global_store_dwordx2 v[52:53], v[10:11], off offset:2048
	s_waitcnt vmcnt(7)
	v_mov_b64_e32 v[10:11], v[96:97]
	v_mov_b64_e32 v[12:13], v[98:99]
	v_pk_mul_f32 v[16:17], v[50:51], v[32:33] op_sel_hi:[0,1]
	v_pk_mul_f32 v[20:21], v[50:51], v[34:35] op_sel_hi:[0,1]
	v_pk_mul_f32 v[10:11], v[16:17], v[10:11]
	v_pk_mul_f32 v[12:13], v[20:21], v[12:13]
	v_cvt_pk_bf16_f32 v10, v10, v11
	v_cvt_pk_bf16_f32 v11, v12, v13
	global_store_dwordx2 v[52:53], v[10:11], off offset:2560
	s_waitcnt vmcnt(7)
	v_mov_b64_e32 v[10:11], v[100:101]
	v_mov_b64_e32 v[12:13], v[102:103]
	v_pk_mul_f32 v[16:17], v[50:51], v[40:41] op_sel_hi:[0,1]
	v_pk_mul_f32 v[20:21], v[50:51], v[42:43] op_sel_hi:[0,1]
	v_pk_mul_f32 v[10:11], v[16:17], v[10:11]
	v_pk_mul_f32 v[12:13], v[20:21], v[12:13]
	v_cvt_pk_bf16_f32 v10, v10, v11
	v_cvt_pk_bf16_f32 v11, v12, v13
	global_store_dwordx2 v[52:53], v[10:11], off offset:3072
	s_waitcnt vmcnt(7)
	v_mov_b64_e32 v[10:11], v[104:105]
	v_mov_b64_e32 v[12:13], v[106:107]
	v_pk_mul_f32 v[14:15], v[50:51], v[36:37] op_sel_hi:[0,1]
	v_pk_mul_f32 v[16:17], v[50:51], v[38:39] op_sel_hi:[0,1]
	v_pk_mul_f32 v[10:11], v[14:15], v[10:11]
	v_pk_mul_f32 v[12:13], v[16:17], v[12:13]
	v_cvt_pk_bf16_f32 v10, v10, v11
	v_cvt_pk_bf16_f32 v11, v12, v13
	global_store_dwordx2 v[52:53], v[10:11], off offset:3584
	s_cbranch_scc0 .LBB0_32

; __global__ void __launch_bounds__(NWAVES * 64, 2) fwd_megakernel(Args args) {
;     ...
;                             const float m0 = MST[mrow], l0 = LST[mrow], m1 = MST[(size_t)2 * SEQ * 16 + mrow], l1 = LST[(size_t)2 * SEQ * 16 + mrow];
;                             const float mn = fmaxf(fmaxf(m, m0), m1);
;                             const float c2 = __builtin_amdgcn_exp2f(m - mn), w0 = l0 * __builtin_amdgcn_exp2f(m0 - mn), w1 = l1 * __builtin_amdgcn_exp2f(m1 - mn);
;                             const float inv = 1.0f / (lt * c2 + w0 + w1);
;                             const float a2 = c2 * inv, a0 = w0 * inv, a1 = w1 * inv;
;                             const bf16_t* p0 = PB + prow + 4 * half; const bf16_t* p1 = p0 + (size_t)SEQ * DM;
; #pragma unroll
;                             for (int blk = 0; blk < 4; ++blk)
; #pragma unroll
;                                 for (int g4 = 0; g4 < 4; ++g4) {
;                                     const u32x2 x0 = *(const u32x2*)(p0 + 32 * blk + 8 * g4), x1 = *(const u32x2*)(p1 + 32 * blk + 8 * g4);
.LBB0_252:
	s_andn2_b64 vcc, exec, s[42:43]
	s_cbranch_vccnz .LBB0_229
	v_readlane_b32 s42, v252, 6
	v_lshlrev_b64 v[2:3], 2, v[2:3]
	v_readlane_b32 s43, v252, 7
	v_lshlrev_b64 v[8:9], 1, v[8:9]
	s_nop 0
	v_lshl_add_u64 v[6:7], s[42:43], 0, v[2:3]
	v_readlane_b32 s42, v252, 8
	v_readlane_b32 s43, v252, 9
	global_load_dword v5, v[6:7], off
	s_nop 0
	v_lshl_add_u64 v[2:3], s[42:43], 0, v[2:3]
	global_load_dword v11, v[2:3], off
	v_add_co_u32_e32 v6, vcc, 0x100000, v6
	s_nop 1
	v_addc_co_u32_e32 v7, vcc, 0, v7, vcc
	global_load_dword v6, v[6:7], off
	v_add_co_u32_e32 v2, vcc, 0x100000, v2
	s_nop 1
	v_addc_co_u32_e32 v3, vcc, 0, v3, vcc
	global_load_dword v10, v[2:3], off
	s_waitcnt vmcnt(1)
	v_max3_f32 v2, v14, v5, v6
	v_sub_f32_e32 v3, v14, v2
	v_exp_f32_e32 v12, v3
	v_sub_f32_e32 v3, v5, v2
	v_sub_f32_e32 v2, v6, v2
	v_exp_f32_e32 v3, v3
	v_exp_f32_e32 v2, v2
	s_waitcnt vmcnt(0)
	v_pk_mul_f32 v[6:7], v[10:11], v[2:3]
	s_nop 0
	v_fma_f32 v2, v4, v12, v7
	v_add_f32_e32 v2, v6, v2
	v_div_scale_f32 v3, s[42:43], v2, v2, 1.0
	v_rcp_f32_e32 v4, v3
	v_readlane_b32 s42, v252, 4
	v_readlane_b32 s43, v252, 5
	v_fma_f32 v5, -v3, v4, 1.0
	v_fmac_f32_e32 v4, v5, v4
	v_div_scale_f32 v5, vcc, 1.0, v2, 1.0
	v_mul_f32_e32 v10, v5, v4
	v_fma_f32 v11, -v3, v10, v5
	v_fmac_f32_e32 v10, v11, v4
	v_fma_f32 v3, -v3, v10, v5
	v_div_fmas_f32 v3, v3, v4, v10
	v_lshl_add_u64 v[10:11], s[42:43], 0, v[8:9]
	v_readlane_b32 s42, v251, 60
	v_div_fixup_f32 v3, v3, v2, 1.0
	v_readlane_b32 s43, v251, 61
	v_mul_f32_e32 v2, v12, v3
	v_lshl_add_u64 v[12:13], v[10:11], 0, v[0:1]
	v_lshl_add_u64 v[8:9], s[42:43], 0, v[8:9]
	s_brev_b32 s42, 64
	v_add_co_u32_e32 v10, vcc, s42, v12
	s_nop 1
	v_addc_co_u32_e32 v11, vcc, 0, v13, vcc
	global_load_dwordx2 v[86:87], v[12:13], off
	global_load_dwordx2 v[88:89], v[10:11], off
	global_load_dwordx2 v[90:91], v[12:13], off offset:16
	global_load_dwordx2 v[92:93], v[10:11], off offset:16
	global_load_dwordx2 v[94:95], v[12:13], off offset:32
	global_load_dwordx2 v[96:97], v[10:11], off offset:32
	global_load_dwordx2 v[98:99], v[12:13], off offset:48
	global_load_dwordx2 v[100:101], v[10:11], off offset:48
	global_load_dwordx2 v[102:103], v[12:13], off offset:64
	global_load_dwordx2 v[104:105], v[10:11], off offset:64
	global_load_dwordx2 v[106:107], v[12:13], off offset:80
	global_load_dwordx2 v[108:109], v[10:11], off offset:80
	global_load_dwordx2 v[110:111], v[12:13], off offset:96
	global_load_dwordx2 v[112:113], v[10:11], off offset:96
	global_load_dwordx2 v[114:115], v[12:13], off offset:112
	global_load_dwordx2 v[116:117], v[10:11], off offset:112
	global_load_dwordx2 v[118:119], v[12:13], off offset:128
	global_load_dwordx2 v[120:121], v[10:11], off offset:128
	global_load_dwordx2 v[122:123], v[12:13], off offset:144
	global_load_dwordx2 v[124:125], v[10:11], off offset:144
	global_load_dwordx2 v[126:127], v[12:13], off offset:160
	global_load_dwordx2 v[128:129], v[10:11], off offset:160
	global_load_dwordx2 v[130:131], v[12:13], off offset:176
	global_load_dwordx2 v[132:133], v[10:11], off offset:176
	global_load_dwordx2 v[134:135], v[12:13], off offset:192
	global_load_dwordx2 v[136:137], v[10:11], off offset:192
	global_load_dwordx2 v[138:139], v[12:13], off offset:208
	global_load_dwordx2 v[140:141], v[10:11], off offset:208
	global_load_dwordx2 v[142:143], v[12:13], off offset:224
	global_load_dwordx2 v[144:145], v[10:11], off offset:224
	global_load_dwordx2 v[146:147], v[12:13], off offset:240
	global_load_dwordx2 v[148:149], v[10:11], off offset:240
	v_mul_f32_e32 v4, v7, v3
	v_pk_mul_f32 v[64:65], v[2:3], v[64:65] op_sel_hi:[0,1]
	v_pk_mul_f32 v[66:67], v[2:3], v[66:67] op_sel_hi:[0,1]
	v_mul_f32_e32 v6, v6, v3
	v_lshl_add_u64 v[8:9], v[8:9], 0, v[0:1]
	v_pk_mul_f32 v[68:69], v[2:3], v[68:69] op_sel_hi:[0,1]
	v_pk_mul_f32 v[48:49], v[2:3], v[48:49] op_sel_hi:[0,1]
	v_pk_mul_f32 v[50:51], v[2:3], v[50:51] op_sel_hi:[0,1]
	v_pk_mul_f32 v[52:53], v[2:3], v[52:53] op_sel_hi:[0,1]
	v_pk_mul_f32 v[32:33], v[2:3], v[32:33] op_sel_hi:[0,1]
	v_pk_mul_f32 v[34:35], v[2:3], v[34:35] op_sel_hi:[0,1]
	v_pk_mul_f32 v[36:37], v[2:3], v[36:37] op_sel_hi:[0,1]
	v_pk_mul_f32 v[16:17], v[2:3], v[16:17] op_sel_hi:[0,1]
	v_pk_mul_f32 v[18:19], v[2:3], v[18:19] op_sel_hi:[0,1]
	v_pk_mul_f32 v[20:21], v[2:3], v[20:21] op_sel_hi:[0,1]
	s_waitcnt vmcnt(0)
; __device__ __forceinline__ unsigned pk2(float lo, float hi) { f32x2 v = {lo, hi}; bf16x2_t b = __builtin_convertvector(v, bf16x2_t); return __builtin_bit_cast(unsigned, b); }
; __global__ void __launch_bounds__(NWAVES * 64, 2) fwd_megakernel(Args args) {
;     ...
; #pragma unroll
;                             for (int blk = 0; blk < 4; ++blk)
; #pragma unroll
;                                 for (int g4 = 0; g4 < 4; ++g4) {
;                                     const u32x2 x0 = *(const u32x2*)(p0 + 32 * blk + 8 * g4), x1 = *(const u32x2*)(p1 + 32 * blk + 8 * g4);
;                                     const float f0[4] = {__uint_as_float(x0.x << 16), __uint_as_float(x0.x & 0xffff0000u), __uint_as_float(x0.y << 16), __uint_as_float(x0.y & 0xffff0000u)};
;                                     const float f1[4] = {__uint_as_float(x1.x << 16), __uint_as_float(x1.x & 0xffff0000u), __uint_as_float(x1.y << 16), __uint_as_float(x1.y & 0xffff0000u)};
;                                     float r[4];
; #pragma unroll
;                                     for (int j = 0; j < 4; ++j) r[j] = O[blk][4 * g4 + j] * a2 + f0[j] * a0 + f1[j] * a1;
;                                     u32x2 w; w.x = pk2(r[0], r[1]); w.y = pk2(r[2], r[3]);
;                                     *(u32x2*)(AO + prow + 32 * blk + 8 * g4 + 4 * half) = w;
	v_mov_b64_e32 v[14:15], v[86:87]
	v_mov_b64_e32 v[80:81], v[88:89]
	v_lshlrev_b32_e32 v82, 16, v14
	v_and_b32_e32 v83, 0xffff0000, v14
	v_lshlrev_b32_e32 v14, 16, v15
	v_and_b32_e32 v15, 0xffff0000, v15
	v_lshlrev_b32_e32 v84, 16, v80
	v_and_b32_e32 v85, 0xffff0000, v80
	v_pk_fma_f32 v[64:65], v[4:5], v[82:83], v[64:65] op_sel_hi:[0,1,1]
	v_lshlrev_b32_e32 v80, 16, v81
	v_and_b32_e32 v81, 0xffff0000, v81
	v_pk_fma_f32 v[14:15], v[4:5], v[14:15], v[66:67] op_sel_hi:[0,1,1]
	v_pk_fma_f32 v[64:65], v[6:7], v[84:85], v[64:65] op_sel_hi:[0,1,1]
	v_pk_fma_f32 v[14:15], v[6:7], v[80:81], v[14:15] op_sel_hi:[0,1,1]
	v_cvt_pk_bf16_f32 v64, v64, v65
	v_cvt_pk_bf16_f32 v65, v14, v15
	global_store_dwordx2 v[8:9], v[64:65], off
	v_mov_b64_e32 v[14:15], v[90:91]
	s_nop 0
	v_mov_b64_e32 v[64:65], v[92:93]
	v_lshlrev_b32_e32 v66, 16, v14
	v_and_b32_e32 v67, 0xffff0000, v14
	v_pk_fma_f32 v[66:67], v[4:5], v[66:67], v[68:69] op_sel_hi:[0,1,1]
	v_lshlrev_b32_e32 v14, 16, v15
	v_and_b32_e32 v15, 0xffff0000, v15
	v_pk_mul_f32 v[68:69], v[2:3], v[70:71] op_sel_hi:[0,1]
	v_lshlrev_b32_e32 v80, 16, v64
	v_and_b32_e32 v81, 0xffff0000, v64
	v_lshlrev_b32_e32 v64, 16, v65
	v_and_b32_e32 v65, 0xffff0000, v65
	v_pk_fma_f32 v[14:15], v[4:5], v[14:15], v[68:69] op_sel_hi:[0,1,1]
	v_pk_fma_f32 v[66:67], v[6:7], v[80:81], v[66:67] op_sel_hi:[0,1,1]
	v_pk_fma_f32 v[14:15], v[6:7], v[64:65], v[14:15] op_sel_hi:[0,1,1]
	v_cvt_pk_bf16_f32 v64, v66, v67
	v_cvt_pk_bf16_f32 v65, v14, v15
	global_store_dwordx2 v[8:9], v[64:65], off offset:16
	v_mov_b64_e32 v[14:15], v[94:95]
	s_nop 0
	v_mov_b64_e32 v[64:65], v[96:97]
	v_pk_mul_f32 v[70:71], v[2:3], v[72:73] op_sel_hi:[0,1]
	v_lshlrev_b32_e32 v66, 16, v14
	v_and_b32_e32 v67, 0xffff0000, v14
	v_lshlrev_b32_e32 v68, 16, v64
	v_and_b32_e32 v69, 0xffff0000, v64
	v_pk_fma_f32 v[66:67], v[4:5], v[66:67], v[70:71] op_sel_hi:[0,1,1]
	v_pk_fma_f32 v[66:67], v[6:7], v[68:69], v[66:67] op_sel_hi:[0,1,1]
	v_lshlrev_b32_e32 v14, 16, v15
	v_and_b32_e32 v15, 0xffff0000, v15
	v_pk_mul_f32 v[68:69], v[2:3], v[74:75] op_sel_hi:[0,1]
	v_lshlrev_b32_e32 v64, 16, v65
	v_and_b32_e32 v65, 0xffff0000, v65
	v_pk_fma_f32 v[14:15], v[4:5], v[14:15], v[68:69] op_sel_hi:[0,1,1]
	v_pk_fma_f32 v[14:15], v[6:7], v[64:65], v[14:15] op_sel_hi:[0,1,1]
	v_cvt_pk_bf16_f32 v64, v66, v67
	v_cvt_pk_bf16_f32 v65, v14, v15
	global_store_dwordx2 v[8:9], v[64:65], off offset:32
	v_mov_b64_e32 v[14:15], v[98:99]
	s_nop 0
	v_mov_b64_e32 v[64:65], v[100:101]
	v_pk_mul_f32 v[70:71], v[2:3], v[76:77] op_sel_hi:[0,1]
	v_lshlrev_b32_e32 v66, 16, v14
	v_and_b32_e32 v67, 0xffff0000, v14
	v_lshlrev_b32_e32 v68, 16, v64
	v_and_b32_e32 v69, 0xffff0000, v64
	v_pk_fma_f32 v[66:67], v[4:5], v[66:67], v[70:71] op_sel_hi:[0,1,1]
	v_pk_fma_f32 v[66:67], v[6:7], v[68:69], v[66:67] op_sel_hi:[0,1,1]
	v_lshlrev_b32_e32 v14, 16, v15
	v_and_b32_e32 v15, 0xffff0000, v15
	v_pk_mul_f32 v[68:69], v[2:3], v[78:79] op_sel_hi:[0,1]
	v_lshlrev_b32_e32 v64, 16, v65
	v_and_b32_e32 v65, 0xffff0000, v65
	v_pk_fma_f32 v[14:15], v[4:5], v[14:15], v[68:69] op_sel_hi:[0,1,1]
	v_pk_fma_f32 v[14:15], v[6:7], v[64:65], v[14:15] op_sel_hi:[0,1,1]
	v_cvt_pk_bf16_f32 v64, v66, v67
	v_cvt_pk_bf16_f32 v65, v14, v15
	global_store_dwordx2 v[8:9], v[64:65], off offset:48
	v_mov_b64_e32 v[14:15], v[102:103]
	s_nop 0
	v_mov_b64_e32 v[64:65], v[104:105]
	v_lshlrev_b32_e32 v66, 16, v14
	v_and_b32_e32 v67, 0xffff0000, v14
	v_lshlrev_b32_e32 v14, 16, v15
	v_and_b32_e32 v15, 0xffff0000, v15
	v_lshlrev_b32_e32 v68, 16, v64
	v_and_b32_e32 v69, 0xffff0000, v64
	v_pk_fma_f32 v[48:49], v[4:5], v[66:67], v[48:49] op_sel_hi:[0,1,1]
	v_lshlrev_b32_e32 v64, 16, v65
	v_and_b32_e32 v65, 0xffff0000, v65
	v_pk_fma_f32 v[14:15], v[4:5], v[14:15], v[50:51] op_sel_hi:[0,1,1]
	v_pk_fma_f32 v[48:49], v[6:7], v[68:69], v[48:49] op_sel_hi:[0,1,1]
	v_pk_fma_f32 v[14:15], v[6:7], v[64:65], v[14:15] op_sel_hi:[0,1,1]
	v_cvt_pk_bf16_f32 v48, v48, v49
	v_cvt_pk_bf16_f32 v49, v14, v15
	global_store_dwordx2 v[8:9], v[48:49], off offset:64
	v_mov_b64_e32 v[14:15], v[106:107]
	s_nop 0
	v_mov_b64_e32 v[48:49], v[108:109]
	v_lshlrev_b32_e32 v50, 16, v14
	v_and_b32_e32 v51, 0xffff0000, v14
	v_pk_fma_f32 v[50:51], v[4:5], v[50:51], v[52:53] op_sel_hi:[0,1,1]
	v_lshlrev_b32_e32 v14, 16, v15
	v_and_b32_e32 v15, 0xffff0000, v15
	v_pk_mul_f32 v[52:53], v[2:3], v[54:55] op_sel_hi:[0,1]
	v_lshlrev_b32_e32 v64, 16, v48
	v_and_b32_e32 v65, 0xffff0000, v48
	v_lshlrev_b32_e32 v48, 16, v49
	v_and_b32_e32 v49, 0xffff0000, v49
	v_pk_fma_f32 v[14:15], v[4:5], v[14:15], v[52:53] op_sel_hi:[0,1,1]
	v_pk_fma_f32 v[50:51], v[6:7], v[64:65], v[50:51] op_sel_hi:[0,1,1]
	v_pk_fma_f32 v[14:15], v[6:7], v[48:49], v[14:15] op_sel_hi:[0,1,1]
	v_cvt_pk_bf16_f32 v48, v50, v51
	v_cvt_pk_bf16_f32 v49, v14, v15
	global_store_dwordx2 v[8:9], v[48:49], off offset:80
	v_mov_b64_e32 v[14:15], v[110:111]
	s_nop 0
	v_mov_b64_e32 v[48:49], v[112:113]
	v_pk_mul_f32 v[54:55], v[2:3], v[56:57] op_sel_hi:[0,1]
	v_lshlrev_b32_e32 v50, 16, v14
	v_and_b32_e32 v51, 0xffff0000, v14
	v_lshlrev_b32_e32 v52, 16, v48
	v_and_b32_e32 v53, 0xffff0000, v48
	v_pk_fma_f32 v[50:51], v[4:5], v[50:51], v[54:55] op_sel_hi:[0,1,1]
	v_pk_fma_f32 v[50:51], v[6:7], v[52:53], v[50:51] op_sel_hi:[0,1,1]
	v_lshlrev_b32_e32 v14, 16, v15
	v_and_b32_e32 v15, 0xffff0000, v15
	v_pk_mul_f32 v[52:53], v[2:3], v[58:59] op_sel_hi:[0,1]
	v_lshlrev_b32_e32 v48, 16, v49
	v_and_b32_e32 v49, 0xffff0000, v49
	v_pk_fma_f32 v[14:15], v[4:5], v[14:15], v[52:53] op_sel_hi:[0,1,1]
	v_pk_fma_f32 v[14:15], v[6:7], v[48:49], v[14:15] op_sel_hi:[0,1,1]
	v_cvt_pk_bf16_f32 v48, v50, v51
	v_cvt_pk_bf16_f32 v49, v14, v15
	global_store_dwordx2 v[8:9], v[48:49], off offset:96
; __device__ __forceinline__ unsigned pk2(float lo, float hi) { f32x2 v = {lo, hi}; bf16x2_t b = __builtin_convertvector(v, bf16x2_t); return __builtin_bit_cast(unsigned, b); }
; __global__ void __launch_bounds__(NWAVES * 64, 2) fwd_megakernel(Args args) {
;     ...
; #pragma unroll
;                             for (int blk = 0; blk < 4; ++blk)
; #pragma unroll
;                                 for (int g4 = 0; g4 < 4; ++g4) {
;                                     const u32x2 x0 = *(const u32x2*)(p0 + 32 * blk + 8 * g4), x1 = *(const u32x2*)(p1 + 32 * blk + 8 * g4);
;                                     const float f0[4] = {__uint_as_float(x0.x << 16), __uint_as_float(x0.x & 0xffff0000u), __uint_as_float(x0.y << 16), __uint_as_float(x0.y & 0xffff0000u)};
;                                     const float f1[4] = {__uint_as_float(x1.x << 16), __uint_as_float(x1.x & 0xffff0000u), __uint_as_float(x1.y << 16), __uint_as_float(x1.y & 0xffff0000u)};
;                                     float r[4];
; #pragma unroll
;                                     for (int j = 0; j < 4; ++j) r[j] = O[blk][4 * g4 + j] * a2 + f0[j] * a0 + f1[j] * a1;
;                                     u32x2 w; w.x = pk2(r[0], r[1]); w.y = pk2(r[2], r[3]);
;                                     *(u32x2*)(AO + prow + 32 * blk + 8 * g4 + 4 * half) = w;
	v_mov_b64_e32 v[14:15], v[114:115]
	s_nop 0
	v_mov_b64_e32 v[48:49], v[116:117]
	v_pk_mul_f32 v[54:55], v[2:3], v[60:61] op_sel_hi:[0,1]
	v_lshlrev_b32_e32 v50, 16, v14
	v_and_b32_e32 v51, 0xffff0000, v14
	v_lshlrev_b32_e32 v52, 16, v48
	v_and_b32_e32 v53, 0xffff0000, v48
	v_pk_fma_f32 v[50:51], v[4:5], v[50:51], v[54:55] op_sel_hi:[0,1,1]
	v_pk_fma_f32 v[50:51], v[6:7], v[52:53], v[50:51] op_sel_hi:[0,1,1]
	v_lshlrev_b32_e32 v14, 16, v15
	v_and_b32_e32 v15, 0xffff0000, v15
	v_pk_mul_f32 v[52:53], v[2:3], v[62:63] op_sel_hi:[0,1]
	v_lshlrev_b32_e32 v48, 16, v49
	v_and_b32_e32 v49, 0xffff0000, v49
	v_pk_fma_f32 v[14:15], v[4:5], v[14:15], v[52:53] op_sel_hi:[0,1,1]
	v_pk_fma_f32 v[14:15], v[6:7], v[48:49], v[14:15] op_sel_hi:[0,1,1]
	v_cvt_pk_bf16_f32 v48, v50, v51
	v_cvt_pk_bf16_f32 v49, v14, v15
	global_store_dwordx2 v[8:9], v[48:49], off offset:112
	v_mov_b64_e32 v[14:15], v[118:119]
	s_nop 0
	v_mov_b64_e32 v[48:49], v[120:121]
	v_lshlrev_b32_e32 v50, 16, v14
	v_and_b32_e32 v51, 0xffff0000, v14
	v_lshlrev_b32_e32 v14, 16, v15
	v_and_b32_e32 v15, 0xffff0000, v15
	v_lshlrev_b32_e32 v52, 16, v48
	v_and_b32_e32 v53, 0xffff0000, v48
	v_pk_fma_f32 v[32:33], v[4:5], v[50:51], v[32:33] op_sel_hi:[0,1,1]
	v_lshlrev_b32_e32 v48, 16, v49
	v_and_b32_e32 v49, 0xffff0000, v49
	v_pk_fma_f32 v[14:15], v[4:5], v[14:15], v[34:35] op_sel_hi:[0,1,1]
	v_pk_fma_f32 v[32:33], v[6:7], v[52:53], v[32:33] op_sel_hi:[0,1,1]
	v_pk_fma_f32 v[14:15], v[6:7], v[48:49], v[14:15] op_sel_hi:[0,1,1]
	v_cvt_pk_bf16_f32 v32, v32, v33
	v_cvt_pk_bf16_f32 v33, v14, v15
	global_store_dwordx2 v[8:9], v[32:33], off offset:128
	v_mov_b64_e32 v[14:15], v[122:123]
	s_nop 0
	v_mov_b64_e32 v[32:33], v[124:125]
	v_lshlrev_b32_e32 v34, 16, v14
	v_and_b32_e32 v35, 0xffff0000, v14
	v_pk_fma_f32 v[34:35], v[4:5], v[34:35], v[36:37] op_sel_hi:[0,1,1]
	v_lshlrev_b32_e32 v14, 16, v15
	v_and_b32_e32 v15, 0xffff0000, v15
	v_pk_mul_f32 v[36:37], v[2:3], v[38:39] op_sel_hi:[0,1]
	v_lshlrev_b32_e32 v48, 16, v32
	v_and_b32_e32 v49, 0xffff0000, v32
	v_lshlrev_b32_e32 v32, 16, v33
	v_and_b32_e32 v33, 0xffff0000, v33
	v_pk_fma_f32 v[14:15], v[4:5], v[14:15], v[36:37] op_sel_hi:[0,1,1]
	v_pk_fma_f32 v[34:35], v[6:7], v[48:49], v[34:35] op_sel_hi:[0,1,1]
	v_pk_fma_f32 v[14:15], v[6:7], v[32:33], v[14:15] op_sel_hi:[0,1,1]
	v_cvt_pk_bf16_f32 v32, v34, v35
	v_cvt_pk_bf16_f32 v33, v14, v15
	global_store_dwordx2 v[8:9], v[32:33], off offset:144
	v_mov_b64_e32 v[14:15], v[126:127]
	s_nop 0
	v_mov_b64_e32 v[32:33], v[128:129]
	v_pk_mul_f32 v[38:39], v[2:3], v[40:41] op_sel_hi:[0,1]
	v_lshlrev_b32_e32 v34, 16, v14
	v_and_b32_e32 v35, 0xffff0000, v14
	v_lshlrev_b32_e32 v36, 16, v32
	v_and_b32_e32 v37, 0xffff0000, v32
	v_pk_fma_f32 v[34:35], v[4:5], v[34:35], v[38:39] op_sel_hi:[0,1,1]
	v_pk_fma_f32 v[34:35], v[6:7], v[36:37], v[34:35] op_sel_hi:[0,1,1]
	v_lshlrev_b32_e32 v14, 16, v15
	v_and_b32_e32 v15, 0xffff0000, v15
	v_pk_mul_f32 v[36:37], v[2:3], v[42:43] op_sel_hi:[0,1]
	v_lshlrev_b32_e32 v32, 16, v33
	v_and_b32_e32 v33, 0xffff0000, v33
	v_pk_fma_f32 v[14:15], v[4:5], v[14:15], v[36:37] op_sel_hi:[0,1,1]
	v_pk_fma_f32 v[14:15], v[6:7], v[32:33], v[14:15] op_sel_hi:[0,1,1]
	v_cvt_pk_bf16_f32 v32, v34, v35
	v_cvt_pk_bf16_f32 v33, v14, v15
	global_store_dwordx2 v[8:9], v[32:33], off offset:160
	v_mov_b64_e32 v[14:15], v[130:131]
	s_nop 0
	v_mov_b64_e32 v[32:33], v[132:133]
	v_pk_mul_f32 v[38:39], v[2:3], v[44:45] op_sel_hi:[0,1]
	v_lshlrev_b32_e32 v34, 16, v14
	v_and_b32_e32 v35, 0xffff0000, v14
	v_lshlrev_b32_e32 v36, 16, v32
	v_and_b32_e32 v37, 0xffff0000, v32
	v_pk_fma_f32 v[34:35], v[4:5], v[34:35], v[38:39] op_sel_hi:[0,1,1]
	v_pk_fma_f32 v[34:35], v[6:7], v[36:37], v[34:35] op_sel_hi:[0,1,1]
	v_lshlrev_b32_e32 v14, 16, v15
; __device__ __forceinline__ unsigned pk2(float lo, float hi) { f32x2 v = {lo, hi}; bf16x2_t b = __builtin_convertvector(v, bf16x2_t); return __builtin_bit_cast(unsigned, b); }
; __global__ void __launch_bounds__(NWAVES * 64, 2) fwd_megakernel(Args args) {
;     ...
; #pragma unroll
;                             for (int blk = 0; blk < 4; ++blk)
; #pragma unroll
;                                 for (int g4 = 0; g4 < 4; ++g4) {
;                                     const u32x2 x0 = *(const u32x2*)(p0 + 32 * blk + 8 * g4), x1 = *(const u32x2*)(p1 + 32 * blk + 8 * g4);
;                                     const float f0[4] = {__uint_as_float(x0.x << 16), __uint_as_float(x0.x & 0xffff0000u), __uint_as_float(x0.y << 16), __uint_as_float(x0.y & 0xffff0000u)};
;                                     const float f1[4] = {__uint_as_float(x1.x << 16), __uint_as_float(x1.x & 0xffff0000u), __uint_as_float(x1.y << 16), __uint_as_float(x1.y & 0xffff0000u)};
;                                     float r[4];
; #pragma unroll
;                                     for (int j = 0; j < 4; ++j) r[j] = O[blk][4 * g4 + j] * a2 + f0[j] * a0 + f1[j] * a1;
;                                     u32x2 w; w.x = pk2(r[0], r[1]); w.y = pk2(r[2], r[3]);
;                                     *(u32x2*)(AO + prow + 32 * blk + 8 * g4 + 4 * half) = w;
	v_and_b32_e32 v15, 0xffff0000, v15
	v_pk_mul_f32 v[36:37], v[2:3], v[46:47] op_sel_hi:[0,1]
	v_lshlrev_b32_e32 v32, 16, v33
	v_and_b32_e32 v33, 0xffff0000, v33
	v_pk_fma_f32 v[14:15], v[4:5], v[14:15], v[36:37] op_sel_hi:[0,1,1]
	v_pk_fma_f32 v[14:15], v[6:7], v[32:33], v[14:15] op_sel_hi:[0,1,1]
	v_cvt_pk_bf16_f32 v32, v34, v35
	v_cvt_pk_bf16_f32 v33, v14, v15
	global_store_dwordx2 v[8:9], v[32:33], off offset:176
	v_mov_b64_e32 v[14:15], v[134:135]
	s_nop 0
	v_mov_b64_e32 v[32:33], v[136:137]
	v_lshlrev_b32_e32 v34, 16, v14
	v_and_b32_e32 v35, 0xffff0000, v14
	v_lshlrev_b32_e32 v14, 16, v15
	v_and_b32_e32 v15, 0xffff0000, v15
	v_lshlrev_b32_e32 v36, 16, v32
	v_and_b32_e32 v37, 0xffff0000, v32
	v_pk_fma_f32 v[16:17], v[4:5], v[34:35], v[16:17] op_sel_hi:[0,1,1]
	v_lshlrev_b32_e32 v32, 16, v33
	v_and_b32_e32 v33, 0xffff0000, v33
	v_pk_fma_f32 v[14:15], v[4:5], v[14:15], v[18:19] op_sel_hi:[0,1,1]
	v_pk_fma_f32 v[16:17], v[6:7], v[36:37], v[16:17] op_sel_hi:[0,1,1]
	v_pk_fma_f32 v[14:15], v[6:7], v[32:33], v[14:15] op_sel_hi:[0,1,1]
	v_cvt_pk_bf16_f32 v16, v16, v17
	v_cvt_pk_bf16_f32 v17, v14, v15
	global_store_dwordx2 v[8:9], v[16:17], off offset:192
	v_mov_b64_e32 v[14:15], v[138:139]
	s_nop 0
	v_mov_b64_e32 v[16:17], v[140:141]
	v_lshlrev_b32_e32 v18, 16, v14
	v_and_b32_e32 v19, 0xffff0000, v14
	v_pk_fma_f32 v[18:19], v[4:5], v[18:19], v[20:21] op_sel_hi:[0,1,1]
	v_lshlrev_b32_e32 v14, 16, v15
	v_and_b32_e32 v15, 0xffff0000, v15
	v_pk_mul_f32 v[20:21], v[2:3], v[22:23] op_sel_hi:[0,1]
	v_lshlrev_b32_e32 v32, 16, v16
	v_and_b32_e32 v33, 0xffff0000, v16
	v_lshlrev_b32_e32 v16, 16, v17
	v_and_b32_e32 v17, 0xffff0000, v17
	v_pk_fma_f32 v[14:15], v[4:5], v[14:15], v[20:21] op_sel_hi:[0,1,1]
	v_pk_fma_f32 v[18:19], v[6:7], v[32:33], v[18:19] op_sel_hi:[0,1,1]
	v_pk_fma_f32 v[14:15], v[6:7], v[16:17], v[14:15] op_sel_hi:[0,1,1]
	v_cvt_pk_bf16_f32 v16, v18, v19
	v_cvt_pk_bf16_f32 v17, v14, v15
	global_store_dwordx2 v[8:9], v[16:17], off offset:208
	v_mov_b64_e32 v[14:15], v[142:143]
	s_nop 0
	v_mov_b64_e32 v[16:17], v[144:145]
	v_pk_mul_f32 v[22:23], v[2:3], v[24:25] op_sel_hi:[0,1]
	v_lshlrev_b32_e32 v18, 16, v14
	v_and_b32_e32 v19, 0xffff0000, v14
	v_lshlrev_b32_e32 v20, 16, v16
	v_and_b32_e32 v21, 0xffff0000, v16
	v_pk_fma_f32 v[18:19], v[4:5], v[18:19], v[22:23] op_sel_hi:[0,1,1]
	v_pk_fma_f32 v[18:19], v[6:7], v[20:21], v[18:19] op_sel_hi:[0,1,1]
	v_lshlrev_b32_e32 v14, 16, v15
	v_and_b32_e32 v15, 0xffff0000, v15
	v_pk_mul_f32 v[20:21], v[2:3], v[26:27] op_sel_hi:[0,1]
	v_lshlrev_b32_e32 v16, 16, v17
	v_and_b32_e32 v17, 0xffff0000, v17
	v_pk_fma_f32 v[14:15], v[4:5], v[14:15], v[20:21] op_sel_hi:[0,1,1]
	v_pk_fma_f32 v[14:15], v[6:7], v[16:17], v[14:15] op_sel_hi:[0,1,1]
	v_cvt_pk_bf16_f32 v16, v18, v19
	v_cvt_pk_bf16_f32 v17, v14, v15
	global_store_dwordx2 v[8:9], v[16:17], off offset:224
	v_mov_b64_e32 v[12:13], v[146:147]
	s_nop 0
	v_mov_b64_e32 v[10:11], v[148:149]
	v_pk_mul_f32 v[18:19], v[2:3], v[28:29] op_sel_hi:[0,1]
	v_pk_mul_f32 v[2:3], v[2:3], v[30:31] op_sel_hi:[0,1]
	v_lshlrev_b32_e32 v14, 16, v12
	v_and_b32_e32 v15, 0xffff0000, v12
	v_lshlrev_b32_e32 v12, 16, v13
	v_and_b32_e32 v13, 0xffff0000, v13
	v_lshlrev_b32_e32 v16, 16, v10
	v_and_b32_e32 v17, 0xffff0000, v10
	v_pk_fma_f32 v[14:15], v[4:5], v[14:15], v[18:19] op_sel_hi:[0,1,1]
	v_lshlrev_b32_e32 v10, 16, v11
	v_and_b32_e32 v11, 0xffff0000, v11
	v_pk_fma_f32 v[2:3], v[4:5], v[12:13], v[2:3] op_sel_hi:[0,1,1]
	v_pk_fma_f32 v[14:15], v[6:7], v[16:17], v[14:15] op_sel_hi:[0,1,1]
	v_pk_fma_f32 v[2:3], v[6:7], v[10:11], v[2:3] op_sel_hi:[0,1,1]
	v_cvt_pk_bf16_f32 v4, v14, v15
	v_cvt_pk_bf16_f32 v5, v2, v3
	global_store_dwordx2 v[8:9], v[4:5], off offset:240
	s_branch .LBB0_229

; __device__ __forceinline__ unsigned pk2(float lo, float hi) { f32x2 v = {lo, hi}; bf16x2_t b = __builtin_convertvector(v, bf16x2_t); return __builtin_bit_cast(unsigned, b); }
; __global__ void __launch_bounds__(NWAVES * 64, 2) fwd_megakernel(Args args) {
;     ...
;                     for (int idx = gw; idx < SEQ * 8; idx += ngw) {
;                         const size_t off = (size_t)(idx >> 3) * 1024 + (idx & 7) * 128 + 2 * lane;
;                         const f32x2 a = *(const f32x2*)(OST + off), b2 = *(const f32x2*)(OST2 + off);
;                         const float v0 = a.x - lam * b2.x, v1 = a.y - lam * b2.y;
;                         const float ss = wave_sum(v0 * v0 + v1 * v1);
;                         const float rs = __builtin_amdgcn_rsqf(ss * (1.0f / 128.f) + EPS) * (1.0f - lambda_init);
;                         *(unsigned*)(AO + (size_t)(idx >> 3) * DM + (idx & 7) * 128 + 2 * lane) = pk2(v0 * rs * sg.x, v1 * rs * sg.y);
;                     }
.LBB0_571:
	s_mul_i32 s98, s92, 3
	s_add_i32 s98, s98, s3
	s_cmp_gt_i32 s98, 0xffff
	s_cbranch_scc1 .Lcmb_single
	v_lshlrev_b32_e32 v12, 1, v0
	v_mov_b32_e32 v13, 0
	s_ashr_i32 s36, s3, 3
	s_ashr_i32 s37, s36, 31
	s_and_b32 s40, s2, 0x380
	s_lshl_b64 s[38:39], s[36:37], 10
	s_or_b32 s38, s38, s40
	v_mov_b32_e32 v9, s39
	v_or_b32_e32 v8, s38, v0
	v_lshlrev_b64 v[8:9], 2, v[8:9]
	v_lshl_add_u64 v[10:11], s[54:55], 0, v[8:9]
	v_lshl_add_u64 v[8:9], s[56:57], 0, v[8:9]
	global_load_dwordx2 v[16:17], v[10:11], off
	global_load_dwordx2 v[14:15], v[8:9], off
	s_lshl_b64 s[36:37], s[36:37], 12
	s_add_u32 s36, s52, s36
	s_addc_u32 s37, s53, s37
	s_lshl_b32 s38, s40, 1
	s_add_u32 s36, s36, s38
	s_addc_u32 s37, s37, 0
	v_lshl_add_u64 v[30:31], s[36:37], 0, v[12:13]
	s_add_i32 s3, s3, s92
	s_add_i32 s2, s2, s58
	s_ashr_i32 s36, s3, 3
	s_ashr_i32 s37, s36, 31
	s_and_b32 s40, s2, 0x380
	s_lshl_b64 s[38:39], s[36:37], 10
	s_or_b32 s38, s38, s40
	v_mov_b32_e32 v9, s39
	v_or_b32_e32 v8, s38, v0
	v_lshlrev_b64 v[8:9], 2, v[8:9]
	v_lshl_add_u64 v[10:11], s[54:55], 0, v[8:9]
	v_lshl_add_u64 v[8:9], s[56:57], 0, v[8:9]
	global_load_dwordx2 v[20:21], v[10:11], off
	global_load_dwordx2 v[18:19], v[8:9], off
	s_lshl_b64 s[36:37], s[36:37], 12
	s_add_u32 s36, s52, s36
	s_addc_u32 s37, s53, s37
	s_lshl_b32 s38, s40, 1
	s_add_u32 s36, s36, s38
	s_addc_u32 s37, s37, 0
	v_lshl_add_u64 v[32:33], s[36:37], 0, v[12:13]
	s_add_i32 s3, s3, s92
	s_add_i32 s2, s2, s58
	s_ashr_i32 s36, s3, 3
	s_ashr_i32 s37, s36, 31
	s_and_b32 s40, s2, 0x380
	s_lshl_b64 s[38:39], s[36:37], 10
	s_or_b32 s38, s38, s40
	v_mov_b32_e32 v9, s39
	v_or_b32_e32 v8, s38, v0
	v_lshlrev_b64 v[8:9], 2, v[8:9]
	v_lshl_add_u64 v[10:11], s[54:55], 0, v[8:9]
	v_lshl_add_u64 v[8:9], s[56:57], 0, v[8:9]
	global_load_dwordx2 v[24:25], v[10:11], off
	global_load_dwordx2 v[22:23], v[8:9], off
	s_lshl_b64 s[36:37], s[36:37], 12
	s_add_u32 s36, s52, s36
	s_addc_u32 s37, s53, s37
	s_lshl_b32 s38, s40, 1
	s_add_u32 s36, s36, s38
	s_addc_u32 s37, s37, 0
	v_lshl_add_u64 v[34:35], s[36:37], 0, v[12:13]
	s_add_i32 s3, s3, s92
	s_add_i32 s2, s2, s58
	s_ashr_i32 s36, s3, 3
	s_ashr_i32 s37, s36, 31
	s_and_b32 s40, s2, 0x380
	s_lshl_b64 s[38:39], s[36:37], 10
	s_or_b32 s38, s38, s40
	v_mov_b32_e32 v9, s39
	v_or_b32_e32 v8, s38, v0
	v_lshlrev_b64 v[8:9], 2, v[8:9]
	v_lshl_add_u64 v[10:11], s[54:55], 0, v[8:9]
	v_lshl_add_u64 v[8:9], s[56:57], 0, v[8:9]
	global_load_dwordx2 v[28:29], v[10:11], off
	global_load_dwordx2 v[26:27], v[8:9], off
	s_lshl_b64 s[36:37], s[36:37], 12
	s_add_u32 s36, s52, s36
	s_addc_u32 s37, s53, s37
	s_lshl_b32 s38, s40, 1
	s_add_u32 s36, s36, s38
	s_addc_u32 s37, s37, 0
	v_lshl_add_u64 v[36:37], s[36:37], 0, v[12:13]
	s_add_i32 s3, s3, s92
	s_add_i32 s2, s2, s58
	s_waitcnt vmcnt(0)
	v_pk_fma_f32 v[14:15], v[2:3], v[14:15], v[16:17] neg_lo:[1,0,0] neg_hi:[1,0,0]
	v_pk_fma_f32 v[18:19], v[2:3], v[18:19], v[20:21] neg_lo:[1,0,0] neg_hi:[1,0,0]
	v_pk_fma_f32 v[22:23], v[2:3], v[22:23], v[24:25] neg_lo:[1,0,0] neg_hi:[1,0,0]
	v_pk_fma_f32 v[26:27], v[2:3], v[26:27], v[28:29] neg_lo:[1,0,0] neg_hi:[1,0,0]
	v_pk_mul_f32 v[16:17], v[14:15], v[14:15]
	v_pk_mul_f32 v[20:21], v[18:19], v[18:19]
	v_pk_mul_f32 v[24:25], v[22:23], v[22:23]
	v_pk_mul_f32 v[28:29], v[26:27], v[26:27]
	v_add_f32_e32 v16, v16, v17
	v_add_f32_e32 v20, v20, v21
	v_add_f32_e32 v24, v24, v25
	v_add_f32_e32 v28, v28, v29
	ds_swizzle_b32 v17, v16 offset:swizzle(SWAP,1)
	ds_swizzle_b32 v21, v20 offset:swizzle(SWAP,1)
	ds_swizzle_b32 v25, v24 offset:swizzle(SWAP,1)
	ds_swizzle_b32 v29, v28 offset:swizzle(SWAP,1)
	s_waitcnt lgkmcnt(0)
	v_add_f32_e32 v16, v16, v17
	v_add_f32_e32 v20, v20, v21
	v_add_f32_e32 v24, v24, v25
	v_add_f32_e32 v28, v28, v29
	ds_swizzle_b32 v17, v16 offset:swizzle(SWAP,2)
	ds_swizzle_b32 v21, v20 offset:swizzle(SWAP,2)
	ds_swizzle_b32 v25, v24 offset:swizzle(SWAP,2)
	ds_swizzle_b32 v29, v28 offset:swizzle(SWAP,2)
	s_waitcnt lgkmcnt(0)
	v_add_f32_e32 v16, v16, v17
	v_add_f32_e32 v20, v20, v21
	v_add_f32_e32 v24, v24, v25
	v_add_f32_e32 v28, v28, v29
	ds_swizzle_b32 v17, v16 offset:swizzle(SWAP,4)
	ds_swizzle_b32 v21, v20 offset:swizzle(SWAP,4)
	ds_swizzle_b32 v25, v24 offset:swizzle(SWAP,4)
	ds_swizzle_b32 v29, v28 offset:swizzle(SWAP,4)
	s_waitcnt lgkmcnt(0)
	v_add_f32_e32 v16, v16, v17
	v_add_f32_e32 v20, v20, v21
	v_add_f32_e32 v24, v24, v25
	v_add_f32_e32 v28, v28, v29
	ds_swizzle_b32 v17, v16 offset:swizzle(SWAP,8)
	ds_swizzle_b32 v21, v20 offset:swizzle(SWAP,8)
	ds_swizzle_b32 v25, v24 offset:swizzle(SWAP,8)
	ds_swizzle_b32 v29, v28 offset:swizzle(SWAP,8)
	s_waitcnt lgkmcnt(0)
	v_add_f32_e32 v16, v16, v17
	v_add_f32_e32 v20, v20, v21
	v_add_f32_e32 v24, v24, v25
	v_add_f32_e32 v28, v28, v29
	ds_swizzle_b32 v17, v16 offset:swizzle(SWAP,16)
	ds_swizzle_b32 v21, v20 offset:swizzle(SWAP,16)
	ds_swizzle_b32 v25, v24 offset:swizzle(SWAP,16)
	ds_swizzle_b32 v29, v28 offset:swizzle(SWAP,16)
	s_waitcnt lgkmcnt(0)
	v_add_f32_e32 v16, v16, v17
	v_add_f32_e32 v20, v20, v21
	v_add_f32_e32 v24, v24, v25
	v_add_f32_e32 v28, v28, v29
	ds_bpermute_b32 v17, v6, v16
	ds_bpermute_b32 v21, v6, v20
	ds_bpermute_b32 v25, v6, v24
	ds_bpermute_b32 v29, v6, v28
	s_waitcnt lgkmcnt(0)
	v_add_f32_e32 v16, v16, v17
	v_add_f32_e32 v20, v20, v21
	v_add_f32_e32 v24, v24, v25
	v_add_f32_e32 v28, v28, v29
	v_fmamk_f32 v16, v16, 0x3c000000, v233
	v_fmamk_f32 v20, v20, 0x3c000000, v233
	v_fmamk_f32 v24, v24, 0x3c000000, v233
	v_fmamk_f32 v28, v28, 0x3c000000, v233
	v_rsq_f32_e32 v16, v16
	v_rsq_f32_e32 v20, v20
	v_rsq_f32_e32 v24, v24
	v_rsq_f32_e32 v28, v28
	v_mul_f32_e32 v16, v7, v16
	v_mul_f32_e32 v20, v7, v20
	v_mul_f32_e32 v24, v7, v24
	v_mul_f32_e32 v28, v7, v28
	v_pk_mul_f32 v[14:15], v[14:15], v[16:17] op_sel_hi:[1,0]
	v_pk_mul_f32 v[18:19], v[18:19], v[20:21] op_sel_hi:[1,0]
	v_pk_mul_f32 v[22:23], v[22:23], v[24:25] op_sel_hi:[1,0]
	v_pk_mul_f32 v[26:27], v[26:27], v[28:29] op_sel_hi:[1,0]
	v_pk_mul_f32 v[14:15], v[4:5], v[14:15]
	v_pk_mul_f32 v[18:19], v[4:5], v[18:19]
	v_pk_mul_f32 v[22:23], v[4:5], v[22:23]
	v_pk_mul_f32 v[26:27], v[4:5], v[26:27]
	v_cvt_pk_bf16_f32 v14, v14, v15
	v_cvt_pk_bf16_f32 v18, v18, v19
	v_cvt_pk_bf16_f32 v22, v22, v23
	v_cvt_pk_bf16_f32 v26, v26, v27
	global_store_dword v[30:31], v14, off
	global_store_dword v[32:33], v18, off
	global_store_dword v[34:35], v22, off
	global_store_dword v[36:37], v26, off
	s_cmp_gt_i32 s3, 0xffff
	s_cbranch_scc0 .LBB0_571
	s_branch .LBB0_572

; #define REFRESH_TID() do { tid = opaque_tid(); lane = tid & 63; wave = __builtin_amdgcn_readfirstlane(tid >> 6); } while (0)
; __global__ void __launch_bounds__(NWAVES * 64, 2) fwd_megakernel(Args args) {
;     ...
;     {
;         REFRESH_TID();
;         const int gw = bid * NWAVES + wave, ngw = G * NWAVES;
;         const float* ssf = SS + (size_t)(4 * DEPTH) * SEQ;
;         const float* gf = args.in[I_FINN];
;         for (int r = gw; r < SEQ; r += ngw) {
;             const float rs = __builtin_amdgcn_rsqf(ssf[r] * (1.0f / DM) + EPS);
;             const f32x4* xr = (const f32x4*)(X + (size_t)r * DM) + lane;
;             f32x4* orow = (f32x4*)(args.out + (size_t)r * DM) + lane;
; #pragma unroll
;             for (int j = 0; j < 8; ++j) { const f32x4 v = xr[64 * j]; const f32x4 gg = *((const f32x4*)gf + lane + 64 * j); orow[64 * j] = v * gg * rs; }
;         }
.LBB0_726:
	v_readlane_b32 s4, v253, 40
	v_readfirstlane_b32 s0, v232
	s_ashr_i32 s0, s0, 6
	s_add_i32 s8, s0, s4
	v_readlane_b32 s20, v254, 40
	s_cmpk_gt_i32 s8, 0x1fff
	v_readlane_b32 s21, v254, 41
	s_cbranch_scc1 .LBB0_729
	v_and_b32_e32 v0, 63, v232
	v_readlane_b32 s12, v254, 20
	v_lshlrev_b32_e32 v0, 4, v0
	v_mov_b32_e32 v1, 0
	v_readlane_b32 s13, v254, 21
	s_mov_b64 s[2:3], 0x1000
	s_ashr_i32 s1, s0, 31
	v_lshl_add_u64 v[2:3], s[12:13], 0, v[0:1]
	v_lshl_add_u64 v[4:5], v[2:3], 0, s[2:3]
	s_mov_b64 s[2:3], 0x1400
	v_lshl_add_u64 v[6:7], v[2:3], 0, s[2:3]
	s_mov_b64 s[2:3], 0x1800
	v_lshl_add_u64 v[8:9], v[2:3], 0, s[2:3]
	s_mov_b64 s[2:3], 0x1c00
	v_lshl_add_u64 v[10:11], v[2:3], 0, s[2:3]
	s_ashr_i32 s3, s4, 31
	s_add_u32 s2, s0, s4
	s_addc_u32 s3, s1, s3
	v_readlane_b32 s16, v254, 24
	s_lshl_b64 s[0:1], s[2:3], 2
	v_readlane_b32 s17, v254, 25
	s_add_u32 s0, s16, s0
	s_addc_u32 s1, s17, s1
	s_add_u32 s0, s0, 0x80000
	s_addc_u32 s1, s1, 0
	s_lshl_b64 s[6:7], s[2:3], 13
	s_add_u32 s2, s16, s6
	v_readlane_b32 s14, v254, 22
	s_addc_u32 s3, s17, s7
	s_lshl_b64 s[4:5], s[92:93], 13
	v_readlane_b32 s15, v254, 23
	s_add_u32 s6, s14, s6
	s_addc_u32 s7, s15, s7
	v_mov_b32_e32 v12, 0x358637bd
	s_mov_b32 s9, 0x15901000
	s_movk_i32 s10, 0x1000
	v_readlane_b32 s18, v254, 26
	v_readlane_b32 s19, v254, 27
	global_load_dwordx4 v[30:33], v[2:3], off
	global_load_dwordx4 v[34:37], v[2:3], off offset:1024
	global_load_dwordx4 v[38:41], v[2:3], off offset:2048
	global_load_dwordx4 v[42:45], v[2:3], off offset:3072
	global_load_dwordx4 v[46:49], v[4:5], off
	global_load_dwordx4 v[50:53], v[6:7], off
	global_load_dwordx4 v[54:57], v[8:9], off
	global_load_dwordx4 v[58:61], v[10:11], off
.LBB0_728:
	global_load_dword v13, v1, s[0:1]
	v_lshl_add_u64 v[22:23], s[2:3], 0, v[0:1]
	v_add_co_u32_e32 v24, vcc, 0x15900000, v22
	s_nop 1
	v_addc_co_u32_e32 v25, vcc, 0, v23, vcc
	v_add_co_u32_e32 v22, vcc, s9, v22
	s_nop 1
	v_addc_co_u32_e32 v23, vcc, 0, v23, vcc
	global_load_dwordx4 v[62:65], v[24:25], off
	global_load_dwordx4 v[66:69], v[24:25], off offset:1024
	global_load_dwordx4 v[70:73], v[24:25], off offset:2048
	global_load_dwordx4 v[74:77], v[24:25], off offset:3072
	global_load_dwordx4 v[78:81], v[22:23], off
	global_load_dwordx4 v[82:85], v[22:23], off offset:1024
	global_load_dwordx4 v[86:89], v[22:23], off offset:2048
	global_load_dwordx4 v[90:93], v[22:23], off offset:3072
	v_lshl_add_u64 v[26:27], s[6:7], 0, v[0:1]
	v_add_co_u32_e32 v24, vcc, s10, v26
	s_nop 1
	v_addc_co_u32_e32 v25, vcc, 0, v27, vcc
	s_add_i32 s8, s8, s92
	s_add_u32 s0, s0, s20
	s_addc_u32 s1, s1, s21
	s_add_u32 s2, s2, s4
	s_addc_u32 s3, s3, s5
	s_add_u32 s6, s6, s4
	s_addc_u32 s7, s7, s5
	s_cmpk_gt_i32 s8, 0x1fff
	s_waitcnt vmcnt(8)
	v_fmamk_f32 v13, v13, 0x3a000000, v12
	v_rsq_f32_e32 v28, v13
	s_waitcnt vmcnt(0)
	v_pk_mul_f32 v[62:63], v[30:31], v[62:63]
	v_pk_mul_f32 v[64:65], v[32:33], v[64:65]
	v_pk_mul_f32 v[66:67], v[34:35], v[66:67]
	v_pk_mul_f32 v[68:69], v[36:37], v[68:69]
	v_pk_mul_f32 v[70:71], v[38:39], v[70:71]
	v_pk_mul_f32 v[72:73], v[40:41], v[72:73]
	v_pk_mul_f32 v[74:75], v[42:43], v[74:75]
	v_pk_mul_f32 v[76:77], v[44:45], v[76:77]
	v_pk_mul_f32 v[78:79], v[46:47], v[78:79]
	v_pk_mul_f32 v[80:81], v[48:49], v[80:81]
	v_pk_mul_f32 v[82:83], v[50:51], v[82:83]
	v_pk_mul_f32 v[84:85], v[52:53], v[84:85]
	v_pk_mul_f32 v[86:87], v[54:55], v[86:87]
	v_pk_mul_f32 v[88:89], v[56:57], v[88:89]
	v_pk_mul_f32 v[90:91], v[58:59], v[90:91]
	v_pk_mul_f32 v[92:93], v[60:61], v[92:93]
	v_pk_mul_f32 v[62:63], v[28:29], v[62:63] op_sel_hi:[0,1]
	v_pk_mul_f32 v[64:65], v[28:29], v[64:65] op_sel_hi:[0,1]
	v_pk_mul_f32 v[66:67], v[28:29], v[66:67] op_sel_hi:[0,1]
	v_pk_mul_f32 v[68:69], v[28:29], v[68:69] op_sel_hi:[0,1]
	v_pk_mul_f32 v[70:71], v[28:29], v[70:71] op_sel_hi:[0,1]
	v_pk_mul_f32 v[72:73], v[28:29], v[72:73] op_sel_hi:[0,1]
	v_pk_mul_f32 v[74:75], v[28:29], v[74:75] op_sel_hi:[0,1]
	v_pk_mul_f32 v[76:77], v[28:29], v[76:77] op_sel_hi:[0,1]
	v_pk_mul_f32 v[78:79], v[28:29], v[78:79] op_sel_hi:[0,1]
	v_pk_mul_f32 v[80:81], v[28:29], v[80:81] op_sel_hi:[0,1]
	v_pk_mul_f32 v[82:83], v[28:29], v[82:83] op_sel_hi:[0,1]
	v_pk_mul_f32 v[84:85], v[28:29], v[84:85] op_sel_hi:[0,1]
	v_pk_mul_f32 v[86:87], v[28:29], v[86:87] op_sel_hi:[0,1]
	v_pk_mul_f32 v[88:89], v[28:29], v[88:89] op_sel_hi:[0,1]
	v_pk_mul_f32 v[90:91], v[28:29], v[90:91] op_sel_hi:[0,1]
	v_pk_mul_f32 v[92:93], v[28:29], v[92:93] op_sel_hi:[0,1]
	global_store_dwordx4 v[26:27], v[62:65], off
	global_store_dwordx4 v[26:27], v[66:69], off offset:1024
	global_store_dwordx4 v[26:27], v[70:73], off offset:2048
	global_store_dwordx4 v[26:27], v[74:77], off offset:3072
	global_store_dwordx4 v[24:25], v[78:81], off
	global_store_dwordx4 v[24:25], v[82:85], off offset:1024
	global_store_dwordx4 v[24:25], v[86:89], off offset:2048
	global_store_dwordx4 v[24:25], v[90:93], off offset:3072
	s_cbranch_scc0 .LBB0_728
